# in-proj epilogue: rope cos/sin fragments double-buffered and prefetched one row group ahead with counted waits
# speedup vs baseline: 1.0330x; 1.0130x over previous
.LBB0_310:
	s_add_u32 s0, s18, 0xfffc0080
	s_addc_u32 s1, s19, -1
	s_add_i32 s27, 0, 0x10000
	v_add_u32_e32 v147, s27, v139
	ds_read_b128 v[152:155], v147
	ds_read_b128 v[156:159], v147 offset:1024
	ds_read_b128 v[160:163], v147 offset:2048
	ds_read_b128 v[164:167], v147 offset:3072
	s_cmp_eq_u32 s26, 12
	s_cselect_b32 s17, s3, s1
	s_cselect_b32 s16, s13, s0
	s_cselect_b32 s1, s20, s25
	s_cselect_b32 s0, s21, s24
	v_lshl_add_u64 v[190:191], s[18:19], 0, v[142:143]
	s_add_i32 m0, s95, 0xc000
	ds_read_b128 v[168:171], v181
	ds_read_b128 v[172:175], v181 offset:1024
	ds_read_b128 v[176:179], v181 offset:2048
	ds_read_b128 v[182:185], v181 offset:3072
	ds_read_b128 v[186:189], v181 offset:4096
	ds_read_b128 v[202:205], v181 offset:5120
	ds_read_b128 v[206:209], v181 offset:6144
	ds_read_b128 v[210:213], v181 offset:7168
	global_load_lds_dwordx4 v[190:191], off
	v_lshl_add_u64 v[190:191], s[18:19], 0, v[144:145]
	s_add_i32 m0, s95, 0xe000
	s_nop 0
	global_load_lds_dwordx4 v[190:191], off
	s_waitcnt lgkmcnt(8)
	s_barrier
	s_waitcnt lgkmcnt(0)
	s_setprio 1
	s_waitcnt lgkmcnt(0)
	v_mfma_f32_16x16x32_bf16 v[124:127], v[152:155], v[168:171], v[124:127]
	v_mfma_f32_16x16x32_bf16 v[120:123], v[160:163], v[168:171], v[120:123]
	v_mfma_f32_16x16x32_bf16 v[108:111], v[152:155], v[176:179], v[108:111]
	v_mfma_f32_16x16x32_bf16 v[104:107], v[160:163], v[176:179], v[104:107]
	v_mfma_f32_16x16x32_bf16 v[92:95], v[152:155], v[186:189], v[92:95]
	v_mfma_f32_16x16x32_bf16 v[88:91], v[160:163], v[186:189], v[88:91]
	v_mfma_f32_16x16x32_bf16 v[76:79], v[152:155], v[206:209], v[76:79]
	v_mfma_f32_16x16x32_bf16 v[72:75], v[160:163], v[206:209], v[72:75]
	v_mfma_f32_16x16x32_bf16 v[124:127], v[156:159], v[172:175], v[124:127]
	v_mfma_f32_16x16x32_bf16 v[120:123], v[164:167], v[172:175], v[120:123]
	v_mfma_f32_16x16x32_bf16 v[108:111], v[156:159], v[182:185], v[108:111]
	v_mfma_f32_16x16x32_bf16 v[104:107], v[164:167], v[182:185], v[104:107]
	v_mfma_f32_16x16x32_bf16 v[92:95], v[156:159], v[202:205], v[92:95]
	v_mfma_f32_16x16x32_bf16 v[88:91], v[164:167], v[202:205], v[88:91]
	v_mfma_f32_16x16x32_bf16 v[76:79], v[156:159], v[210:213], v[76:79]
	v_mfma_f32_16x16x32_bf16 v[72:75], v[164:167], v[210:213], v[72:75]
	s_setprio 0
	s_barrier
	s_add_i32 s36, 0, 0x14000
	s_add_i32 s27, s27, s94
	v_add_u32_e32 v147, s36, v139
	v_lshl_add_u64 v[190:191], s[0:1], 0, v[132:133]
	s_mov_b32 m0, s27
	ds_read_b128 v[214:217], v147
	ds_read_b128 v[218:221], v147 offset:1024
	ds_read_b128 v[238:241], v147 offset:2048
	ds_read_b128 v[242:245], v147 offset:3072
	global_load_lds_dwordx4 v[190:191], off
	v_lshl_add_u64 v[222:223], s[0:1], 0, v[128:129]
	s_add_i32 m0, s27, 0x2000
	s_nop 0
	global_load_lds_dwordx4 v[222:223], off
	s_barrier
	s_waitcnt lgkmcnt(0)
	s_setprio 1
	s_waitcnt lgkmcnt(0)
	v_mfma_f32_16x16x32_bf16 v[116:119], v[214:217], v[168:171], v[116:119]
	v_mfma_f32_16x16x32_bf16 v[112:115], v[238:241], v[168:171], v[112:115]
	v_mfma_f32_16x16x32_bf16 v[100:103], v[214:217], v[176:179], v[100:103]
	v_mfma_f32_16x16x32_bf16 v[96:99], v[238:241], v[176:179], v[96:99]
	v_mfma_f32_16x16x32_bf16 v[84:87], v[214:217], v[186:189], v[84:87]
	v_mfma_f32_16x16x32_bf16 v[80:83], v[238:241], v[186:189], v[80:83]
	v_mfma_f32_16x16x32_bf16 v[68:71], v[214:217], v[206:209], v[68:71]
	v_mfma_f32_16x16x32_bf16 v[64:67], v[238:241], v[206:209], v[64:67]
	v_mfma_f32_16x16x32_bf16 v[116:119], v[218:221], v[172:175], v[116:119]
	v_mfma_f32_16x16x32_bf16 v[112:115], v[242:245], v[172:175], v[112:115]
	v_mfma_f32_16x16x32_bf16 v[100:103], v[218:221], v[182:185], v[100:103]
	v_mfma_f32_16x16x32_bf16 v[96:99], v[242:245], v[182:185], v[96:99]
	v_mfma_f32_16x16x32_bf16 v[84:87], v[218:221], v[202:205], v[84:87]
	v_mfma_f32_16x16x32_bf16 v[80:83], v[242:245], v[202:205], v[80:83]
	v_mfma_f32_16x16x32_bf16 v[68:71], v[218:221], v[210:213], v[68:71]
	v_mfma_f32_16x16x32_bf16 v[64:67], v[242:245], v[210:213], v[64:67]
	s_setprio 0
	s_mov_b32 m0, s95
	v_lshl_add_u64 v[246:247], s[16:17], 0, v[134:135]
	s_barrier
	ds_read_b128 v[168:171], v181 offset:16384
	ds_read_b128 v[172:175], v181 offset:17408
	ds_read_b128 v[176:179], v181 offset:18432
	ds_read_b128 v[182:185], v181 offset:19456
	ds_read_b128 v[186:189], v181 offset:20480
	ds_read_b128 v[202:205], v181 offset:21504
	ds_read_b128 v[206:209], v181 offset:22528
	ds_read_b128 v[210:213], v181 offset:23552
	global_load_lds_dwordx4 v[246:247], off
	v_lshl_add_u64 v[248:249], s[16:17], 0, v[130:131]
	s_mov_b32 m0, s96
	s_nop 0
	global_load_lds_dwordx4 v[248:249], off
	s_barrier
	s_waitcnt lgkmcnt(0)
	s_setprio 1
	s_waitcnt lgkmcnt(0)
	v_mfma_f32_16x16x32_bf16 v[60:63], v[152:155], v[168:171], v[60:63]
	v_mfma_f32_16x16x32_bf16 v[56:59], v[160:163], v[168:171], v[56:59]
	v_mfma_f32_16x16x32_bf16 v[44:47], v[152:155], v[176:179], v[44:47]
	v_mfma_f32_16x16x32_bf16 v[40:43], v[160:163], v[176:179], v[40:43]
	v_mfma_f32_16x16x32_bf16 v[28:31], v[152:155], v[186:189], v[28:31]
	v_mfma_f32_16x16x32_bf16 v[24:27], v[160:163], v[186:189], v[24:27]
	v_mfma_f32_16x16x32_bf16 v[12:15], v[152:155], v[206:209], v[12:15]
	v_mfma_f32_16x16x32_bf16 v[8:11], v[160:163], v[206:209], v[8:11]
	v_mfma_f32_16x16x32_bf16 v[60:63], v[156:159], v[172:175], v[60:63]
	v_mfma_f32_16x16x32_bf16 v[56:59], v[164:167], v[172:175], v[56:59]
	v_mfma_f32_16x16x32_bf16 v[44:47], v[156:159], v[182:185], v[44:47]
	v_mfma_f32_16x16x32_bf16 v[40:43], v[164:167], v[182:185], v[40:43]
	v_mfma_f32_16x16x32_bf16 v[28:31], v[156:159], v[202:205], v[28:31]
	v_mfma_f32_16x16x32_bf16 v[24:27], v[164:167], v[202:205], v[24:27]
	v_mfma_f32_16x16x32_bf16 v[12:15], v[156:159], v[210:213], v[12:15]
	v_mfma_f32_16x16x32_bf16 v[8:11], v[164:167], v[210:213], v[8:11]
	s_setprio 0
	s_barrier
	s_add_u32 s28, s0, 0x40000
	s_addc_u32 s29, s1, 0
	s_add_i32 s27, s36, s94
	v_lshl_add_u64 v[152:153], s[28:29], 0, v[132:133]
	s_mov_b32 m0, s27
	s_nop 0
	global_load_lds_dwordx4 v[152:153], off
	v_lshl_add_u64 v[152:153], s[28:29], 0, v[128:129]
	s_add_i32 m0, s27, 0x2000
	s_nop 0
	global_load_lds_dwordx4 v[152:153], off
	s_waitcnt vmcnt(6)
	s_barrier
	s_setprio 1
	v_mfma_f32_16x16x32_bf16 v[52:55], v[214:217], v[168:171], v[52:55]
	v_mfma_f32_16x16x32_bf16 v[48:51], v[238:241], v[168:171], v[48:51]
	v_mfma_f32_16x16x32_bf16 v[36:39], v[214:217], v[176:179], v[36:39]
	v_mfma_f32_16x16x32_bf16 v[32:35], v[238:241], v[176:179], v[32:35]
	v_mfma_f32_16x16x32_bf16 v[20:23], v[214:217], v[186:189], v[20:23]
	v_mfma_f32_16x16x32_bf16 v[16:19], v[238:241], v[186:189], v[16:19]
	v_mfma_f32_16x16x32_bf16 v[4:7], v[214:217], v[206:209], v[4:7]
	v_mfma_f32_16x16x32_bf16 v[0:3], v[238:241], v[206:209], v[0:3]
	v_mfma_f32_16x16x32_bf16 v[52:55], v[218:221], v[172:175], v[52:55]
	v_mfma_f32_16x16x32_bf16 v[48:51], v[242:245], v[172:175], v[48:51]
	v_mfma_f32_16x16x32_bf16 v[36:39], v[218:221], v[182:185], v[36:39]
	v_mfma_f32_16x16x32_bf16 v[32:35], v[242:245], v[182:185], v[32:35]
	v_mfma_f32_16x16x32_bf16 v[20:23], v[218:221], v[202:205], v[20:23]
	v_mfma_f32_16x16x32_bf16 v[16:19], v[242:245], v[202:205], v[16:19]
	v_mfma_f32_16x16x32_bf16 v[4:7], v[218:221], v[210:213], v[4:7]
	v_mfma_f32_16x16x32_bf16 v[0:3], v[242:245], v[210:213], v[0:3]
	s_setprio 0
	s_add_i32 s27, 0, 0x18000
	v_add_u32_e32 v147, s27, v139
	s_barrier
	ds_read_b128 v[152:155], v147
	ds_read_b128 v[156:159], v147 offset:1024
	ds_read_b128 v[160:163], v147 offset:2048
	ds_read_b128 v[164:167], v147 offset:3072
	s_add_u32 s16, s16, 0x40000
	s_addc_u32 s17, s17, 0
	s_mov_b32 m0, s97
	v_lshl_add_u64 v[214:215], s[16:17], 0, v[134:135]
	ds_read_b128 v[168:171], v181 offset:32768
	ds_read_b128 v[172:175], v181 offset:33792
	ds_read_b128 v[176:179], v181 offset:34816
	ds_read_b128 v[182:185], v181 offset:35840
	ds_read_b128 v[186:189], v181 offset:36864
	ds_read_b128 v[202:205], v181 offset:37888
	ds_read_b128 v[206:209], v181 offset:38912
	ds_read_b128 v[210:213], v181 offset:39936
	global_load_lds_dwordx4 v[214:215], off
	v_lshl_add_u64 v[214:215], s[16:17], 0, v[130:131]
	s_mov_b32 m0, s4
	s_nop 0
	global_load_lds_dwordx4 v[214:215], off
	s_waitcnt lgkmcnt(8)
	s_barrier
	s_waitcnt lgkmcnt(0)
	s_setprio 1
	s_waitcnt lgkmcnt(0)
	v_mfma_f32_16x16x32_bf16 v[124:127], v[152:155], v[168:171], v[124:127]
	v_mfma_f32_16x16x32_bf16 v[120:123], v[160:163], v[168:171], v[120:123]
	v_mfma_f32_16x16x32_bf16 v[108:111], v[152:155], v[176:179], v[108:111]
	v_mfma_f32_16x16x32_bf16 v[104:107], v[160:163], v[176:179], v[104:107]
	v_mfma_f32_16x16x32_bf16 v[92:95], v[152:155], v[186:189], v[92:95]
	v_mfma_f32_16x16x32_bf16 v[88:91], v[160:163], v[186:189], v[88:91]
	v_mfma_f32_16x16x32_bf16 v[76:79], v[152:155], v[206:209], v[76:79]
	v_mfma_f32_16x16x32_bf16 v[72:75], v[160:163], v[206:209], v[72:75]
	v_mfma_f32_16x16x32_bf16 v[124:127], v[156:159], v[172:175], v[124:127]
	v_mfma_f32_16x16x32_bf16 v[120:123], v[164:167], v[172:175], v[120:123]
	v_mfma_f32_16x16x32_bf16 v[108:111], v[156:159], v[182:185], v[108:111]
	v_mfma_f32_16x16x32_bf16 v[104:107], v[164:167], v[182:185], v[104:107]
	v_mfma_f32_16x16x32_bf16 v[92:95], v[156:159], v[202:205], v[92:95]
	v_mfma_f32_16x16x32_bf16 v[88:91], v[164:167], v[202:205], v[88:91]
	v_mfma_f32_16x16x32_bf16 v[76:79], v[156:159], v[210:213], v[76:79]
	v_mfma_f32_16x16x32_bf16 v[72:75], v[164:167], v[210:213], v[72:75]
	s_setprio 0
	s_barrier
	s_add_i32 s16, 0, 0x1c000
	s_add_i32 s17, s27, s94
	v_add_u32_e32 v147, s16, v139
	v_lshl_add_u64 v[190:191], v[190:191], 0, s[30:31]
	s_mov_b32 m0, s17
	ds_read_b128 v[214:217], v147
	ds_read_b128 v[218:221], v147 offset:1024
	ds_read_b128 v[238:241], v147 offset:2048
	ds_read_b128 v[242:245], v147 offset:3072
	global_load_lds_dwordx4 v[190:191], off
	v_lshl_add_u64 v[190:191], v[222:223], 0, s[30:31]
	s_add_i32 m0, s17, 0x2000
	s_nop 0
	global_load_lds_dwordx4 v[190:191], off
	s_barrier
	s_waitcnt lgkmcnt(0)
	s_setprio 1
	s_waitcnt lgkmcnt(0)
	v_mfma_f32_16x16x32_bf16 v[116:119], v[214:217], v[168:171], v[116:119]
	v_mfma_f32_16x16x32_bf16 v[112:115], v[238:241], v[168:171], v[112:115]
	v_mfma_f32_16x16x32_bf16 v[100:103], v[214:217], v[176:179], v[100:103]
	v_mfma_f32_16x16x32_bf16 v[96:99], v[238:241], v[176:179], v[96:99]
	v_mfma_f32_16x16x32_bf16 v[84:87], v[214:217], v[186:189], v[84:87]
	v_mfma_f32_16x16x32_bf16 v[80:83], v[238:241], v[186:189], v[80:83]
	v_mfma_f32_16x16x32_bf16 v[68:71], v[214:217], v[206:209], v[68:71]
	v_mfma_f32_16x16x32_bf16 v[64:67], v[238:241], v[206:209], v[64:67]
	v_mfma_f32_16x16x32_bf16 v[116:119], v[218:221], v[172:175], v[116:119]
	v_mfma_f32_16x16x32_bf16 v[112:115], v[242:245], v[172:175], v[112:115]
	v_mfma_f32_16x16x32_bf16 v[100:103], v[218:221], v[182:185], v[100:103]
	v_mfma_f32_16x16x32_bf16 v[96:99], v[242:245], v[182:185], v[96:99]
	v_mfma_f32_16x16x32_bf16 v[84:87], v[218:221], v[202:205], v[84:87]
	v_mfma_f32_16x16x32_bf16 v[80:83], v[242:245], v[202:205], v[80:83]
	v_mfma_f32_16x16x32_bf16 v[68:71], v[218:221], v[210:213], v[68:71]
	v_mfma_f32_16x16x32_bf16 v[64:67], v[242:245], v[210:213], v[64:67]
	s_setprio 0
	s_mov_b32 m0, s6
	v_lshl_add_u64 v[190:191], v[246:247], 0, s[30:31]
	s_barrier
	ds_read_b128 v[168:171], v181 offset:49152
	ds_read_b128 v[172:175], v181 offset:50176
	ds_read_b128 v[176:179], v181 offset:51200
	ds_read_b128 v[182:185], v181 offset:52224
	ds_read_b128 v[186:189], v181 offset:53248
	ds_read_b128 v[202:205], v181 offset:54272
	ds_read_b128 v[206:209], v181 offset:55296
	ds_read_b128 v[210:213], v181 offset:56320
	global_load_lds_dwordx4 v[190:191], off
	v_lshl_add_u64 v[190:191], v[248:249], 0, s[30:31]
	s_mov_b32 m0, s7
	s_nop 0
	global_load_lds_dwordx4 v[190:191], off
	s_barrier
	s_waitcnt lgkmcnt(0)
	s_setprio 1
	s_waitcnt lgkmcnt(0)
	v_mfma_f32_16x16x32_bf16 v[60:63], v[152:155], v[168:171], v[60:63]
	v_mfma_f32_16x16x32_bf16 v[56:59], v[160:163], v[168:171], v[56:59]
	v_mfma_f32_16x16x32_bf16 v[44:47], v[152:155], v[176:179], v[44:47]
	v_mfma_f32_16x16x32_bf16 v[40:43], v[160:163], v[176:179], v[40:43]
	v_mfma_f32_16x16x32_bf16 v[28:31], v[152:155], v[186:189], v[28:31]
	v_mfma_f32_16x16x32_bf16 v[24:27], v[160:163], v[186:189], v[24:27]
	v_mfma_f32_16x16x32_bf16 v[12:15], v[152:155], v[206:209], v[12:15]
	v_mfma_f32_16x16x32_bf16 v[8:11], v[160:163], v[206:209], v[8:11]
	v_mfma_f32_16x16x32_bf16 v[60:63], v[156:159], v[172:175], v[60:63]
	v_mfma_f32_16x16x32_bf16 v[56:59], v[164:167], v[172:175], v[56:59]
	v_mfma_f32_16x16x32_bf16 v[44:47], v[156:159], v[182:185], v[44:47]
	v_mfma_f32_16x16x32_bf16 v[40:43], v[164:167], v[182:185], v[40:43]
	v_mfma_f32_16x16x32_bf16 v[28:31], v[156:159], v[202:205], v[28:31]
	v_mfma_f32_16x16x32_bf16 v[24:27], v[164:167], v[202:205], v[24:27]
	v_mfma_f32_16x16x32_bf16 v[12:15], v[156:159], v[210:213], v[12:15]
	v_mfma_f32_16x16x32_bf16 v[8:11], v[164:167], v[210:213], v[8:11]
	s_setprio 0
	s_barrier
	s_add_u32 s0, s0, 0x40080
	s_addc_u32 s1, s1, 0
	s_add_i32 s16, s16, s94
	v_lshl_add_u64 v[152:153], s[0:1], 0, v[132:133]
	s_mov_b32 m0, s16
	s_nop 0
	global_load_lds_dwordx4 v[152:153], off
	v_lshl_add_u64 v[152:153], s[0:1], 0, v[128:129]
	s_add_i32 m0, s16, 0x2000
	s_nop 0
	global_load_lds_dwordx4 v[152:153], off
	s_waitcnt vmcnt(6)
	s_barrier
	s_setprio 1
	v_mfma_f32_16x16x32_bf16 v[52:55], v[214:217], v[168:171], v[52:55]
	v_mfma_f32_16x16x32_bf16 v[48:51], v[238:241], v[168:171], v[48:51]
	v_mfma_f32_16x16x32_bf16 v[36:39], v[214:217], v[176:179], v[36:39]
	v_mfma_f32_16x16x32_bf16 v[32:35], v[238:241], v[176:179], v[32:35]
	v_mfma_f32_16x16x32_bf16 v[20:23], v[214:217], v[186:189], v[20:23]
	v_mfma_f32_16x16x32_bf16 v[16:19], v[238:241], v[186:189], v[16:19]
	v_mfma_f32_16x16x32_bf16 v[4:7], v[214:217], v[206:209], v[4:7]
	v_mfma_f32_16x16x32_bf16 v[0:3], v[238:241], v[206:209], v[0:3]
	v_mfma_f32_16x16x32_bf16 v[52:55], v[218:221], v[172:175], v[52:55]
	v_mfma_f32_16x16x32_bf16 v[48:51], v[242:245], v[172:175], v[48:51]
	v_mfma_f32_16x16x32_bf16 v[36:39], v[218:221], v[182:185], v[36:39]
	v_mfma_f32_16x16x32_bf16 v[32:35], v[242:245], v[182:185], v[32:35]
	v_mfma_f32_16x16x32_bf16 v[20:23], v[218:221], v[202:205], v[20:23]
	v_mfma_f32_16x16x32_bf16 v[16:19], v[242:245], v[202:205], v[16:19]
	v_mfma_f32_16x16x32_bf16 v[4:7], v[218:221], v[210:213], v[4:7]
	v_mfma_f32_16x16x32_bf16 v[0:3], v[242:245], v[210:213], v[0:3]
	s_setprio 0
	s_add_i32 s26, s26, 2
	s_add_u32 s18, s18, 0x100
	s_addc_u32 s19, s19, 0
	s_add_u32 s24, s24, 0x100
	s_addc_u32 s25, s25, 0
	s_cmp_gt_u32 s26, 13
	s_barrier
	s_cbranch_scc0 .LBB0_310
	s_cmp_lt_i32 s2, 64
	s_cselect_b64 s[44:45], -1, 0
	s_lshl_b32 s26, s2, 8
	s_add_i32 s26, s26, s5
	s_add_i32 s0, s33, -2
	s_cmp_lt_u32 s0, 4
	s_mov_b64 s[24:25], s[66:67]
	s_cselect_b64 s[50:51], -1, 0
	s_cmp_gt_u32 s33, 3
	v_lshlrev_b32_e32 v162, 2, v138
	v_mov_b32_e32 v163, v197
	s_cselect_b64 s[42:43], -1, 0
	s_cmp_gt_u32 s0, 3
	v_lshl_add_u64 v[152:153], s[24:25], 0, v[162:163]
	s_mov_b64 s[0:1], 0x4500000
	v_bitop3_b32 v151, s26, v229, v137 bitop3:0xc8
	v_lshl_add_u64 v[156:157], v[152:153], 0, s[0:1]
	s_mov_b64 s[0:1], 0x4580800
	v_cndmask_b32_e64 v147, v141, v151, s[44:45]
	v_lshl_add_u64 v[154:155], v[152:153], 0, s[0:1]
	v_lshlrev_b32_e32 v196, 8, v147
	s_mov_b64 s[18:19], s[10:11]
	s_mov_b64 s[52:53], s[60:61]
	v_lshl_add_u64 v[170:171], v[156:157], 0, v[196:197]
	v_lshl_add_u64 v[172:173], v[154:155], 0, v[196:197]
	s_cbranch_scc1 .LBB0_313
	s_mov_b64 s[98:99], 0x1000
	s_mov_b64 s[100:101], 0x5000
	global_load_dwordx4 v[202:205], v[172:173], off
	global_load_dwordx4 v[206:209], v[170:171], off
	v_lshl_add_u64 v[218:219], v[172:173], 0, s[98:99]
	v_lshl_add_u64 v[220:221], v[170:171], 0, s[98:99]
	global_load_dwordx4 v[210:213], v[218:219], off
	global_load_dwordx4 v[214:217], v[220:221], off
	s_waitcnt vmcnt(2)
	v_pk_mul_f32 v[152:153], v[122:123], v[204:205]
	v_pk_mul_f32 v[168:169], v[120:121], v[202:203]
	v_pk_mul_f32 v[160:161], v[126:127], v[204:205]
	v_pk_mul_f32 v[158:159], v[124:125], v[202:203]
	v_pk_fma_f32 v[126:127], v[126:127], v[208:209], v[152:153] neg_lo:[0,0,1] neg_hi:[0,0,1]
	v_pk_fma_f32 v[124:125], v[124:125], v[206:207], v[168:169] neg_lo:[0,0,1] neg_hi:[0,0,1]
	v_pk_fma_f32 v[122:123], v[122:123], v[208:209], v[160:161]
	v_pk_fma_f32 v[120:121], v[120:121], v[206:207], v[158:159]
	v_pk_mul_f32 v[152:153], v[124:125], s[14:15] op_sel_hi:[1,0]
	v_pk_mul_f32 v[158:159], v[126:127], s[14:15] op_sel_hi:[1,0]
	v_pk_mul_f32 v[160:161], v[120:121], s[14:15] op_sel_hi:[1,0]
	v_pk_mul_f32 v[164:165], v[122:123], s[14:15] op_sel_hi:[1,0]
	v_cndmask_b32_e64 v121, v121, v161, s[42:43]
	v_cndmask_b32_e64 v123, v123, v165, s[42:43]
	v_cndmask_b32_e64 v122, v122, v164, s[42:43]
	v_cndmask_b32_e64 v120, v120, v160, s[42:43]
	v_cndmask_b32_e64 v127, v127, v159, s[42:43]
	v_cndmask_b32_e64 v126, v126, v158, s[42:43]
	v_cndmask_b32_e64 v125, v125, v153, s[42:43]
	v_cndmask_b32_e64 v124, v124, v152, s[42:43]

.LBB0_338:
	s_or_b32 s2, s26, 16
	v_bitop3_b32 v151, s2, v233, v137 bitop3:0xc8
	v_cndmask_b32_e64 v112, v141, v151, s[44:45]
	v_lshlrev_b32_e32 v196, 8, v112
	v_lshl_add_u64 v[118:119], v[156:157], 0, v[196:197]
	s_and_b64 vcc, exec, s[52:53]
	v_lshl_add_u64 v[122:123], v[154:155], 0, v[196:197]
	s_cbranch_vccnz .LBB0_340
	v_lshl_add_u64 v[218:219], v[122:123], 0, s[98:99]
	v_lshl_add_u64 v[220:221], v[118:119], 0, s[98:99]
	global_load_dwordx4 v[202:205], v[218:219], off
	global_load_dwordx4 v[206:209], v[220:221], off
	s_cmp_lg_u64 s[42:43], 0
	s_cbranch_scc1 .Lrope_wk_1
	s_waitcnt vmcnt(6)
	s_branch .Lrope_wd_1
.Lrope_wk_1:
	s_waitcnt vmcnt(22)
.Lrope_wd_1:
	v_pk_mul_f32 v[116:117], v[106:107], v[212:213]
	v_pk_mul_f32 v[120:121], v[104:105], v[210:211]
	v_pk_mul_f32 v[114:115], v[110:111], v[212:213]
	v_pk_mul_f32 v[112:113], v[108:109], v[210:211]
	v_pk_fma_f32 v[110:111], v[110:111], v[216:217], v[116:117] neg_lo:[0,0,1] neg_hi:[0,0,1]
	v_pk_fma_f32 v[108:109], v[108:109], v[214:215], v[120:121] neg_lo:[0,0,1] neg_hi:[0,0,1]
	v_pk_fma_f32 v[106:107], v[106:107], v[216:217], v[114:115]
	v_pk_fma_f32 v[104:105], v[104:105], v[214:215], v[112:113]
	v_pk_mul_f32 v[112:113], v[108:109], s[14:15] op_sel_hi:[1,0]
	v_pk_mul_f32 v[114:115], v[110:111], s[14:15] op_sel_hi:[1,0]
	v_pk_mul_f32 v[116:117], v[104:105], s[14:15] op_sel_hi:[1,0]
	v_pk_mul_f32 v[120:121], v[106:107], s[14:15] op_sel_hi:[1,0]
	v_cndmask_b32_e64 v105, v105, v117, s[42:43]
	v_cndmask_b32_e64 v107, v107, v121, s[42:43]
	v_cndmask_b32_e64 v106, v106, v120, s[42:43]
	v_cndmask_b32_e64 v104, v104, v116, s[42:43]
	v_cndmask_b32_e64 v111, v111, v115, s[42:43]
	v_cndmask_b32_e64 v110, v110, v114, s[42:43]
	v_cndmask_b32_e64 v109, v109, v113, s[42:43]
	v_cndmask_b32_e64 v108, v108, v112, s[42:43]

.LBB0_356:
	s_and_b64 vcc, exec, s[52:53]
	s_cbranch_vccnz .LBB0_358
	v_pk_mul_f32 v[118:119], v[98:99], v[212:213]
	v_pk_mul_f32 v[122:123], v[96:97], v[210:211]
	v_pk_mul_f32 v[106:107], v[102:103], v[212:213]
	v_pk_mul_f32 v[104:105], v[100:101], v[210:211]
	v_pk_fma_f32 v[102:103], v[102:103], v[216:217], v[118:119] neg_lo:[0,0,1] neg_hi:[0,0,1]
	v_pk_fma_f32 v[100:101], v[100:101], v[214:215], v[122:123] neg_lo:[0,0,1] neg_hi:[0,0,1]
	v_pk_fma_f32 v[98:99], v[98:99], v[216:217], v[106:107]
	v_pk_fma_f32 v[96:97], v[96:97], v[214:215], v[104:105]
	v_pk_mul_f32 v[104:105], v[100:101], s[14:15] op_sel_hi:[1,0]
	v_pk_mul_f32 v[106:107], v[102:103], s[14:15] op_sel_hi:[1,0]
	v_pk_mul_f32 v[108:109], v[96:97], s[14:15] op_sel_hi:[1,0]
	v_pk_mul_f32 v[110:111], v[98:99], s[14:15] op_sel_hi:[1,0]
	v_cndmask_b32_e64 v97, v97, v109, s[42:43]
	v_cndmask_b32_e64 v99, v99, v111, s[42:43]
	v_cndmask_b32_e64 v98, v98, v110, s[42:43]
	v_cndmask_b32_e64 v96, v96, v108, s[42:43]
	v_cndmask_b32_e64 v103, v103, v107, s[42:43]
	v_cndmask_b32_e64 v102, v102, v106, s[42:43]
	v_cndmask_b32_e64 v101, v101, v105, s[42:43]
	v_cndmask_b32_e64 v100, v100, v104, s[42:43]

.LBB0_364:
	s_or_b32 s2, s26, 32
	v_bitop3_b32 v115, s2, v234, v137 bitop3:0xc8
	v_cndmask_b32_e64 v96, v141, v115, s[44:45]
	v_lshlrev_b32_e32 v196, 8, v96
	v_lshl_add_u64 v[102:103], v[156:157], 0, v[196:197]
	s_and_b64 vcc, exec, s[52:53]
	v_lshl_add_u64 v[106:107], v[154:155], 0, v[196:197]
	s_cbranch_vccnz .LBB0_366
	v_lshl_add_u64 v[218:219], v[106:107], 0, s[98:99]
	v_lshl_add_u64 v[220:221], v[102:103], 0, s[98:99]
	global_load_dwordx4 v[210:213], v[218:219], off
	global_load_dwordx4 v[214:217], v[220:221], off
	s_cmp_lg_u64 s[42:43], 0
	s_cbranch_scc1 .Lrope_wk_2
	s_waitcnt vmcnt(6)
	s_branch .Lrope_wd_2

.Lrope_wd_2:
	v_pk_mul_f32 v[100:101], v[90:91], v[204:205]
	v_pk_mul_f32 v[104:105], v[88:89], v[202:203]
	v_pk_mul_f32 v[98:99], v[94:95], v[204:205]
	v_pk_mul_f32 v[96:97], v[92:93], v[202:203]
	v_pk_fma_f32 v[94:95], v[94:95], v[208:209], v[100:101] neg_lo:[0,0,1] neg_hi:[0,0,1]
	v_pk_fma_f32 v[92:93], v[92:93], v[206:207], v[104:105] neg_lo:[0,0,1] neg_hi:[0,0,1]
	v_pk_fma_f32 v[90:91], v[90:91], v[208:209], v[98:99]
	v_pk_fma_f32 v[88:89], v[88:89], v[206:207], v[96:97]
	v_pk_mul_f32 v[96:97], v[92:93], s[14:15] op_sel_hi:[1,0]
	v_pk_mul_f32 v[98:99], v[94:95], s[14:15] op_sel_hi:[1,0]
	v_pk_mul_f32 v[100:101], v[88:89], s[14:15] op_sel_hi:[1,0]
	v_pk_mul_f32 v[104:105], v[90:91], s[14:15] op_sel_hi:[1,0]
	v_cndmask_b32_e64 v89, v89, v101, s[42:43]
	v_cndmask_b32_e64 v91, v91, v105, s[42:43]
	v_cndmask_b32_e64 v90, v90, v104, s[42:43]
	v_cndmask_b32_e64 v88, v88, v100, s[42:43]
	v_cndmask_b32_e64 v95, v95, v99, s[42:43]
	v_cndmask_b32_e64 v94, v94, v98, s[42:43]
	v_cndmask_b32_e64 v93, v93, v97, s[42:43]
	v_cndmask_b32_e64 v92, v92, v96, s[42:43]

.LBB0_390:
	s_or_b32 s2, s26, 48
	v_bitop3_b32 v101, s2, v235, v137 bitop3:0xc8
	v_cndmask_b32_e64 v80, v141, v101, s[44:45]
	v_lshlrev_b32_e32 v196, 8, v80
	v_lshl_add_u64 v[88:89], v[156:157], 0, v[196:197]
	s_and_b64 vcc, exec, s[52:53]
	v_lshl_add_u64 v[92:93], v[154:155], 0, v[196:197]
	s_cbranch_vccnz .LBB0_392
	v_lshl_add_u64 v[218:219], v[92:93], 0, s[100:101]
	v_lshl_add_u64 v[220:221], v[88:89], 0, s[100:101]
	global_load_dwordx4 v[202:205], v[218:219], off
	global_load_dwordx4 v[206:209], v[220:221], off
	s_cmp_lg_u64 s[42:43], 0
	s_cbranch_scc1 .Lrope_wk_3
	s_waitcnt vmcnt(6)
	s_branch .Lrope_wd_3

.Lrope_wd_3:
	v_pk_mul_f32 v[90:91], v[74:75], v[212:213]
	v_pk_mul_f32 v[94:95], v[72:73], v[210:211]
	v_pk_mul_f32 v[82:83], v[78:79], v[212:213]
	v_pk_mul_f32 v[80:81], v[76:77], v[210:211]
	v_pk_fma_f32 v[78:79], v[78:79], v[216:217], v[90:91] neg_lo:[0,0,1] neg_hi:[0,0,1]
	v_pk_fma_f32 v[76:77], v[76:77], v[214:215], v[94:95] neg_lo:[0,0,1] neg_hi:[0,0,1]
	v_pk_fma_f32 v[74:75], v[74:75], v[216:217], v[82:83]
	v_pk_fma_f32 v[72:73], v[72:73], v[214:215], v[80:81]
	v_pk_mul_f32 v[80:81], v[76:77], s[14:15] op_sel_hi:[1,0]
	v_pk_mul_f32 v[82:83], v[78:79], s[14:15] op_sel_hi:[1,0]
	v_pk_mul_f32 v[84:85], v[72:73], s[14:15] op_sel_hi:[1,0]
	v_pk_mul_f32 v[86:87], v[74:75], s[14:15] op_sel_hi:[1,0]
	v_cndmask_b32_e64 v73, v73, v85, s[42:43]
	v_cndmask_b32_e64 v75, v75, v87, s[42:43]
	v_cndmask_b32_e64 v74, v74, v86, s[42:43]
	v_cndmask_b32_e64 v72, v72, v84, s[42:43]
	v_cndmask_b32_e64 v79, v79, v83, s[42:43]
	v_cndmask_b32_e64 v78, v78, v82, s[42:43]
	v_cndmask_b32_e64 v77, v77, v81, s[42:43]
	v_cndmask_b32_e64 v76, v76, v80, s[42:43]

.LBB0_408:
	s_or_b64 exec, exec, s[2:3]
	s_and_b64 vcc, exec, s[52:53]
	s_cbranch_vccnz .LBB0_410
	v_pk_mul_f32 v[88:89], v[66:67], v[212:213]
	v_pk_mul_f32 v[92:93], v[64:65], v[210:211]
	v_pk_mul_f32 v[74:75], v[70:71], v[212:213]
	v_pk_mul_f32 v[72:73], v[68:69], v[210:211]
	v_pk_fma_f32 v[70:71], v[70:71], v[216:217], v[88:89] neg_lo:[0,0,1] neg_hi:[0,0,1]
	v_pk_fma_f32 v[68:69], v[68:69], v[214:215], v[92:93] neg_lo:[0,0,1] neg_hi:[0,0,1]
	v_pk_fma_f32 v[66:67], v[66:67], v[216:217], v[74:75]
	v_pk_fma_f32 v[64:65], v[64:65], v[214:215], v[72:73]
	v_pk_mul_f32 v[72:73], v[68:69], s[14:15] op_sel_hi:[1,0]
	v_pk_mul_f32 v[74:75], v[70:71], s[14:15] op_sel_hi:[1,0]
	v_pk_mul_f32 v[76:77], v[64:65], s[14:15] op_sel_hi:[1,0]
	v_pk_mul_f32 v[78:79], v[66:67], s[14:15] op_sel_hi:[1,0]
	v_cndmask_b32_e64 v65, v65, v77, s[42:43]
	v_cndmask_b32_e64 v67, v67, v79, s[42:43]
	v_cndmask_b32_e64 v66, v66, v78, s[42:43]
	v_cndmask_b32_e64 v64, v64, v76, s[42:43]
	v_cndmask_b32_e64 v71, v71, v75, s[42:43]
	v_cndmask_b32_e64 v70, v70, v74, s[42:43]
	v_cndmask_b32_e64 v69, v69, v73, s[42:43]
	v_cndmask_b32_e64 v68, v68, v72, s[42:43]

.LBB0_416:
	s_or_b64 exec, exec, s[2:3]
	s_add_i32 s2, s26, 0x80
	v_bitop3_b32 v85, s2, v229, v137 bitop3:0xc8
	v_cndmask_b32_e64 v64, v141, v85, s[44:45]
	v_lshlrev_b32_e32 v196, 8, v64
	v_lshl_add_u64 v[70:71], v[156:157], 0, v[196:197]
	s_and_b64 vcc, exec, s[52:53]
	v_lshl_add_u64 v[74:75], v[154:155], 0, v[196:197]
	s_cbranch_vccnz .LBB0_418
	v_lshl_add_u64 v[218:219], v[74:75], 0, s[98:99]
	v_lshl_add_u64 v[220:221], v[70:71], 0, s[98:99]
	global_load_dwordx4 v[210:213], v[218:219], off
	global_load_dwordx4 v[214:217], v[220:221], off
	s_cmp_lg_u64 s[42:43], 0
	s_cbranch_scc1 .Lrope_wk_4
	s_waitcnt vmcnt(6)
	s_branch .Lrope_wd_4

.Lrope_wd_4:
	v_pk_mul_f32 v[68:69], v[58:59], v[204:205]
	v_pk_mul_f32 v[72:73], v[56:57], v[202:203]
	v_pk_mul_f32 v[66:67], v[62:63], v[204:205]
	v_pk_mul_f32 v[64:65], v[60:61], v[202:203]
	v_pk_fma_f32 v[62:63], v[62:63], v[208:209], v[68:69] neg_lo:[0,0,1] neg_hi:[0,0,1]
	v_pk_fma_f32 v[60:61], v[60:61], v[206:207], v[72:73] neg_lo:[0,0,1] neg_hi:[0,0,1]
	v_pk_fma_f32 v[58:59], v[58:59], v[208:209], v[66:67]
	v_pk_fma_f32 v[56:57], v[56:57], v[206:207], v[64:65]
	v_pk_mul_f32 v[64:65], v[60:61], s[14:15] op_sel_hi:[1,0]
	v_pk_mul_f32 v[66:67], v[62:63], s[14:15] op_sel_hi:[1,0]
	v_pk_mul_f32 v[68:69], v[56:57], s[14:15] op_sel_hi:[1,0]
	v_pk_mul_f32 v[72:73], v[58:59], s[14:15] op_sel_hi:[1,0]
	v_cndmask_b32_e64 v57, v57, v69, s[42:43]
	v_cndmask_b32_e64 v59, v59, v73, s[42:43]
	v_cndmask_b32_e64 v58, v58, v72, s[42:43]
	v_cndmask_b32_e64 v56, v56, v68, s[42:43]
	v_cndmask_b32_e64 v63, v63, v67, s[42:43]
	v_cndmask_b32_e64 v62, v62, v66, s[42:43]
	v_cndmask_b32_e64 v61, v61, v65, s[42:43]
	v_cndmask_b32_e64 v60, v60, v64, s[42:43]

.LBB0_442:
	s_add_i32 s16, s26, 0x90
	v_bitop3_b32 v67, s16, v233, v137 bitop3:0xc8
	v_cndmask_b32_e64 v48, v141, v67, s[44:45]
	v_lshlrev_b32_e32 v196, 8, v48
	v_lshl_add_u64 v[54:55], v[156:157], 0, v[196:197]
	s_and_b64 vcc, exec, s[52:53]
	v_lshl_add_u64 v[58:59], v[154:155], 0, v[196:197]
	s_cbranch_vccnz .LBB0_444
	v_lshl_add_u64 v[218:219], v[58:59], 0, s[98:99]
	v_lshl_add_u64 v[220:221], v[54:55], 0, s[98:99]
	global_load_dwordx4 v[202:205], v[218:219], off
	global_load_dwordx4 v[206:209], v[220:221], off
	s_cmp_lg_u64 s[42:43], 0
	s_cbranch_scc1 .Lrope_wk_5
	s_waitcnt vmcnt(6)
	s_branch .Lrope_wd_5

.Lrope_wd_5:
	v_pk_mul_f32 v[52:53], v[42:43], v[212:213]
	v_pk_mul_f32 v[56:57], v[40:41], v[210:211]
	v_pk_mul_f32 v[50:51], v[46:47], v[212:213]
	v_pk_mul_f32 v[48:49], v[44:45], v[210:211]
	v_pk_fma_f32 v[46:47], v[46:47], v[216:217], v[52:53] neg_lo:[0,0,1] neg_hi:[0,0,1]
	v_pk_fma_f32 v[44:45], v[44:45], v[214:215], v[56:57] neg_lo:[0,0,1] neg_hi:[0,0,1]
	v_pk_fma_f32 v[42:43], v[42:43], v[216:217], v[50:51]
	v_pk_fma_f32 v[40:41], v[40:41], v[214:215], v[48:49]
	v_pk_mul_f32 v[48:49], v[44:45], s[14:15] op_sel_hi:[1,0]
	v_pk_mul_f32 v[50:51], v[46:47], s[14:15] op_sel_hi:[1,0]
	v_pk_mul_f32 v[52:53], v[40:41], s[14:15] op_sel_hi:[1,0]
	v_pk_mul_f32 v[56:57], v[42:43], s[14:15] op_sel_hi:[1,0]
	v_cndmask_b32_e64 v41, v41, v53, s[42:43]
	v_cndmask_b32_e64 v43, v43, v57, s[42:43]
	v_cndmask_b32_e64 v42, v42, v56, s[42:43]
	v_cndmask_b32_e64 v40, v40, v52, s[42:43]
	v_cndmask_b32_e64 v47, v47, v51, s[42:43]
	v_cndmask_b32_e64 v46, v46, v50, s[42:43]
	v_cndmask_b32_e64 v45, v45, v49, s[42:43]
	v_cndmask_b32_e64 v44, v44, v48, s[42:43]

.LBB0_460:
	s_and_b64 vcc, exec, s[52:53]
	s_cbranch_vccnz .LBB0_462
	v_pk_mul_f32 v[54:55], v[34:35], v[212:213]
	v_pk_mul_f32 v[58:59], v[32:33], v[210:211]
	v_pk_mul_f32 v[42:43], v[38:39], v[212:213]
	v_pk_mul_f32 v[40:41], v[36:37], v[210:211]
	v_pk_fma_f32 v[38:39], v[38:39], v[216:217], v[54:55] neg_lo:[0,0,1] neg_hi:[0,0,1]
	v_pk_fma_f32 v[36:37], v[36:37], v[214:215], v[58:59] neg_lo:[0,0,1] neg_hi:[0,0,1]
	v_pk_fma_f32 v[34:35], v[34:35], v[216:217], v[42:43]
	v_pk_fma_f32 v[32:33], v[32:33], v[214:215], v[40:41]
	v_pk_mul_f32 v[40:41], v[36:37], s[14:15] op_sel_hi:[1,0]
	v_pk_mul_f32 v[42:43], v[38:39], s[14:15] op_sel_hi:[1,0]
	v_pk_mul_f32 v[44:45], v[32:33], s[14:15] op_sel_hi:[1,0]
	v_pk_mul_f32 v[46:47], v[34:35], s[14:15] op_sel_hi:[1,0]
	v_cndmask_b32_e64 v33, v33, v45, s[42:43]
	v_cndmask_b32_e64 v35, v35, v47, s[42:43]
	v_cndmask_b32_e64 v34, v34, v46, s[42:43]
	v_cndmask_b32_e64 v32, v32, v44, s[42:43]
	v_cndmask_b32_e64 v39, v39, v43, s[42:43]
	v_cndmask_b32_e64 v38, v38, v42, s[42:43]
	v_cndmask_b32_e64 v37, v37, v41, s[42:43]
	v_cndmask_b32_e64 v36, v36, v40, s[42:43]

.LBB0_468:
	s_add_i32 s16, s26, 0xa0
	v_bitop3_b32 v51, s16, v234, v137 bitop3:0xc8
	v_cndmask_b32_e64 v32, v141, v51, s[44:45]
	v_lshlrev_b32_e32 v196, 8, v32
	v_lshl_add_u64 v[38:39], v[156:157], 0, v[196:197]
	s_and_b64 vcc, exec, s[52:53]
	v_lshl_add_u64 v[42:43], v[154:155], 0, v[196:197]
	s_cbranch_vccnz .LBB0_470
	v_lshl_add_u64 v[218:219], v[42:43], 0, s[98:99]
	v_lshl_add_u64 v[220:221], v[38:39], 0, s[98:99]
	global_load_dwordx4 v[210:213], v[218:219], off
	global_load_dwordx4 v[214:217], v[220:221], off
	s_cmp_lg_u64 s[42:43], 0
	s_cbranch_scc1 .Lrope_wk_6
	s_waitcnt vmcnt(6)
	s_branch .Lrope_wd_6

.Lrope_wd_6:
	v_pk_mul_f32 v[36:37], v[26:27], v[204:205]
	v_pk_mul_f32 v[40:41], v[24:25], v[202:203]
	v_pk_mul_f32 v[34:35], v[30:31], v[204:205]
	v_pk_mul_f32 v[32:33], v[28:29], v[202:203]
	v_pk_fma_f32 v[30:31], v[30:31], v[208:209], v[36:37] neg_lo:[0,0,1] neg_hi:[0,0,1]
	v_pk_fma_f32 v[28:29], v[28:29], v[206:207], v[40:41] neg_lo:[0,0,1] neg_hi:[0,0,1]
	v_pk_fma_f32 v[26:27], v[26:27], v[208:209], v[34:35]
	v_pk_fma_f32 v[24:25], v[24:25], v[206:207], v[32:33]
	v_pk_mul_f32 v[32:33], v[28:29], s[14:15] op_sel_hi:[1,0]
	v_pk_mul_f32 v[34:35], v[30:31], s[14:15] op_sel_hi:[1,0]
	v_pk_mul_f32 v[36:37], v[24:25], s[14:15] op_sel_hi:[1,0]
	v_pk_mul_f32 v[40:41], v[26:27], s[14:15] op_sel_hi:[1,0]
	v_cndmask_b32_e64 v25, v25, v37, s[42:43]
	v_cndmask_b32_e64 v27, v27, v41, s[42:43]
	v_cndmask_b32_e64 v26, v26, v40, s[42:43]
	v_cndmask_b32_e64 v24, v24, v36, s[42:43]
	v_cndmask_b32_e64 v31, v31, v35, s[42:43]
	v_cndmask_b32_e64 v30, v30, v34, s[42:43]
	v_cndmask_b32_e64 v29, v29, v33, s[42:43]
	v_cndmask_b32_e64 v28, v28, v32, s[42:43]

.LBB0_494:
	s_addk_i32 s26, 0xb0
	v_bitop3_b32 v35, s26, v235, v137 bitop3:0xc8
	v_cndmask_b32_e64 v16, v141, v35, s[44:45]
	v_lshlrev_b32_e32 v196, 8, v16
	v_lshl_add_u64 v[22:23], v[156:157], 0, v[196:197]
	s_and_b64 vcc, exec, s[52:53]
	v_lshl_add_u64 v[26:27], v[154:155], 0, v[196:197]
	s_cbranch_vccnz .LBB0_496
	s_cmp_lg_u64 s[42:43], 0
	s_cbranch_scc1 .Lrope_wk_7
	s_waitcnt vmcnt(4)
	s_branch .Lrope_wd_7
.Lrope_wk_7:
	s_waitcnt vmcnt(20)
.Lrope_wd_7:
	v_pk_mul_f32 v[20:21], v[10:11], v[212:213]
	v_pk_mul_f32 v[24:25], v[8:9], v[210:211]
	v_pk_mul_f32 v[18:19], v[14:15], v[212:213]
	v_pk_mul_f32 v[16:17], v[12:13], v[210:211]
	v_pk_fma_f32 v[14:15], v[14:15], v[216:217], v[20:21] neg_lo:[0,0,1] neg_hi:[0,0,1]
	v_pk_fma_f32 v[12:13], v[12:13], v[214:215], v[24:25] neg_lo:[0,0,1] neg_hi:[0,0,1]
	v_pk_fma_f32 v[10:11], v[10:11], v[216:217], v[18:19]
	v_pk_fma_f32 v[8:9], v[8:9], v[214:215], v[16:17]
	v_pk_mul_f32 v[16:17], v[12:13], s[14:15] op_sel_hi:[1,0]
	v_pk_mul_f32 v[18:19], v[14:15], s[14:15] op_sel_hi:[1,0]
	v_pk_mul_f32 v[20:21], v[8:9], s[14:15] op_sel_hi:[1,0]
	v_pk_mul_f32 v[24:25], v[10:11], s[14:15] op_sel_hi:[1,0]
	v_cndmask_b32_e64 v9, v9, v21, s[42:43]
	v_cndmask_b32_e64 v11, v11, v25, s[42:43]
	v_cndmask_b32_e64 v10, v10, v24, s[42:43]
	v_cndmask_b32_e64 v8, v8, v20, s[42:43]
	v_cndmask_b32_e64 v15, v15, v19, s[42:43]
	v_cndmask_b32_e64 v14, v14, v18, s[42:43]
	v_cndmask_b32_e64 v13, v13, v17, s[42:43]
	v_cndmask_b32_e64 v12, v12, v16, s[42:43]

.LBB0_512:
	s_or_b64 exec, exec, s[2:3]
	s_and_b64 vcc, exec, s[52:53]
	s_cbranch_vccnz .LBB0_514
	v_pk_mul_f32 v[22:23], v[2:3], v[212:213]
	v_pk_mul_f32 v[26:27], v[0:1], v[210:211]
	v_pk_mul_f32 v[10:11], v[6:7], v[212:213]
	v_pk_mul_f32 v[8:9], v[4:5], v[210:211]
	v_pk_fma_f32 v[6:7], v[6:7], v[216:217], v[22:23] neg_lo:[0,0,1] neg_hi:[0,0,1]
	v_pk_fma_f32 v[4:5], v[4:5], v[214:215], v[26:27] neg_lo:[0,0,1] neg_hi:[0,0,1]
	v_pk_fma_f32 v[2:3], v[2:3], v[216:217], v[10:11]
	v_pk_fma_f32 v[0:1], v[0:1], v[214:215], v[8:9]
	v_pk_mul_f32 v[8:9], v[4:5], s[14:15] op_sel_hi:[1,0]
	v_pk_mul_f32 v[10:11], v[6:7], s[14:15] op_sel_hi:[1,0]
	v_pk_mul_f32 v[12:13], v[0:1], s[14:15] op_sel_hi:[1,0]
	v_pk_mul_f32 v[14:15], v[2:3], s[14:15] op_sel_hi:[1,0]
	v_cndmask_b32_e64 v1, v1, v13, s[42:43]
	v_cndmask_b32_e64 v3, v3, v15, s[42:43]
	v_cndmask_b32_e64 v2, v2, v14, s[42:43]
	v_cndmask_b32_e64 v0, v0, v12, s[42:43]
	v_cndmask_b32_e64 v7, v7, v11, s[42:43]
	v_cndmask_b32_e64 v6, v6, v10, s[42:43]
	v_cndmask_b32_e64 v5, v5, v9, s[42:43]
	v_cndmask_b32_e64 v4, v4, v8, s[42:43]

	.amdhsa_kernel _Z14fwd_megakernel6Params
		.amdhsa_group_segment_fixed_size 0
		.amdhsa_private_segment_fixed_size 0
		.amdhsa_kernarg_size 384
		.amdhsa_user_sgpr_count 2
		.amdhsa_user_sgpr_dispatch_ptr 0
		.amdhsa_user_sgpr_queue_ptr 0
		.amdhsa_user_sgpr_kernarg_segment_ptr 1
		.amdhsa_user_sgpr_dispatch_id 0
		.amdhsa_user_sgpr_kernarg_preload_length 0
		.amdhsa_user_sgpr_kernarg_preload_offset 0
		.amdhsa_user_sgpr_private_segment_size 0
		.amdhsa_uses_dynamic_stack 0
		.amdhsa_enable_private_segment 0
		.amdhsa_system_sgpr_workgroup_id_x 1
		.amdhsa_system_sgpr_workgroup_id_y 0
		.amdhsa_system_sgpr_workgroup_id_z 0
		.amdhsa_system_sgpr_workgroup_info 0
		.amdhsa_system_vgpr_workitem_id 2
		.amdhsa_next_free_vgpr 256
		.amdhsa_next_free_sgpr 102
		.amdhsa_accum_offset 256
		.amdhsa_reserve_vcc 1
		.amdhsa_float_round_mode_32 0
		.amdhsa_float_round_mode_16_64 0
		.amdhsa_float_denorm_mode_32 3
		.amdhsa_float_denorm_mode_16_64 3
		.amdhsa_dx10_clamp 1
		.amdhsa_ieee_mode 1
		.amdhsa_fp16_overflow 0
		.amdhsa_tg_split 0
		.amdhsa_exception_fp_ieee_invalid_op 0
		.amdhsa_exception_fp_denorm_src 0
		.amdhsa_exception_fp_ieee_div_zero 0
		.amdhsa_exception_fp_ieee_overflow 0
		.amdhsa_exception_fp_ieee_underflow 0
		.amdhsa_exception_fp_ieee_inexact 0
		.amdhsa_exception_int_div_zero 0
	.end_amdhsa_kernel

amdhsa.kernels:
  - .agpr_count:     0
    .args:
      - .offset:         0
        .size:           128
        .value_kind:     by_value
      - .offset:         128
        .size:           4
        .value_kind:     hidden_block_count_x
      - .offset:         132
        .size:           4
        .value_kind:     hidden_block_count_y
      - .offset:         136
        .size:           4
        .value_kind:     hidden_block_count_z
      - .offset:         140
        .size:           2
        .value_kind:     hidden_group_size_x
      - .offset:         142
        .size:           2
        .value_kind:     hidden_group_size_y
      - .offset:         144
        .size:           2
        .value_kind:     hidden_group_size_z
      - .offset:         146
        .size:           2
        .value_kind:     hidden_remainder_x
      - .offset:         148
        .size:           2
        .value_kind:     hidden_remainder_y
      - .offset:         150
        .size:           2
        .value_kind:     hidden_remainder_z
      - .offset:         168
        .size:           8
        .value_kind:     hidden_global_offset_x
      - .offset:         176
        .size:           8
        .value_kind:     hidden_global_offset_y
      - .offset:         184
        .size:           8
        .value_kind:     hidden_global_offset_z
      - .offset:         192
        .size:           2
        .value_kind:     hidden_grid_dims
      - .offset:         216
        .size:           8
        .value_kind:     hidden_multigrid_sync_arg
      - .offset:         248
        .size:           4
        .value_kind:     hidden_dynamic_lds_size
    .group_segment_fixed_size: 0
    .kernarg_segment_align: 8
    .kernarg_segment_size: 384
    .language:       OpenCL C
    .language_version:
      - 2
      - 0
    .max_flat_workgroup_size: 512
    .name:           _Z14fwd_megakernel6Params
    .private_segment_fixed_size: 0
    .sgpr_count:     108
    .sgpr_spill_count: 120
    .symbol:         _Z14fwd_megakernel6Params.kd
    .uniform_work_group_size: 1
    .uses_dynamic_stack: false
    .vgpr_count:     256
    .vgpr_spill_count: 0
    .wavefront_size: 64
